# X3+H3 epilogues de-serialized (batched gate loads), X3 cseg prefix reused across items of same head
# baseline (speedup 1.0000x reference)
; #define LAS __attribute__((address_space(3)))
; __global__ void __launch_bounds__(NTHREADS, 2) fwd_megakernel(Args a) {
;     extern __shared__ __attribute__((aligned(16))) unsigned char ldsg[];
;     LAS unsigned char* lds = (LAS unsigned char*)ldsg;
;     cg::grid_group grid = cg::this_grid();
;     const int G = gridDim.x;
;     unsigned char* ws = a.ws;
;     ...
;     volatile LAS unsigned* xst = (volatile LAS unsigned*)(lds + LDS_XST);
;     if (threadIdx.x < 2) xst[threadIdx.x] = 0u;
;     __syncthreads();
;     const XcdBarrier xbar = xcd_barrier_post((unsigned*)(ws + WS_CTL), xst);
_Z14fwd_megakernel4Args:
	s_mov_b32 s28, s2
	s_load_dwordx16 s[36:51], s[0:1], 0x40
	s_load_dwordx4 s[52:55], s[0:1], 0x80
	s_load_dword s2, s[0:1], 0x90
	s_add_u32 s4, s0, 0x88
	v_and_b32_e32 v178, 0x3ff, v0
	s_addc_u32 s5, s1, 0
	v_cmp_gt_u32_e32 vcc, 2, v178
	s_waitcnt lgkmcnt(0)
	v_writelane_b32 v255, s2, 0
	s_mov_b32 s98, -1
	s_and_saveexec_b64 s[2:3], vcc
	v_lshl_add_u32 v1, v178, 2, 0
	v_add_u32_e32 v1, 0x24000, v1
	v_mov_b32_e32 v2, 0
	ds_write_b32 v1, v2
	s_or_b64 exec, exec, s[2:3]
	s_waitcnt lgkmcnt(0)
	s_barrier
	s_getreg_b32 s2, hwreg(HW_REG_XCC_ID, 0, 4)
	s_and_b32 s29, s2, 15
	v_cmp_eq_u32_e64 s[26:27], 0, v178
	s_and_saveexec_b64 s[2:3], s[26:27]
	s_cbranch_execz .LBB0_5
	s_mov_b64 s[6:7], exec
	v_mbcnt_lo_u32_b32 v1, s6, 0
	v_mbcnt_hi_u32_b32 v1, s7, v1
	v_cmp_eq_u32_e32 vcc, 0, v1
	s_and_b64 s[8:9], exec, vcc
	s_mov_b64 exec, s[8:9]
	s_cbranch_execz .LBB0_5
	s_lshl_b32 s8, s29, 8
	s_bcnt1_i32_b64 s6, s[6:7]
	v_mov_b32_e32 v1, s8
	v_mov_b32_e32 v2, s6
	global_atomic_add v1, v2, s[50:51] offset:1024

; __device__ __forceinline__ void phase_x3(const Args& a, unsigned char* ldsg, int G) {
;     ...
;     for (int item = blockIdx.x; item < NITEM; item += G) {
;         const int qb = (TR / QB) - 1 - item / NH, h = item % NH, R0 = qb * QB; const size_t hb = (size_t)h * HD;
;         __syncthreads();
;         if (wid == 0) {
;             float run = 0.f;
;             for (int s0 = 0; s0 < NCHUNK; s0 += 64) { const int sg = s0 + lane; float v = sg < NCHUNK ? SEG[sg * 16 + h] : 0.f; float x = v;
; #pragma unroll
;                 for (int o = 1; o < 64; o <<= 1) { const float y = __shfl_up(x, o); if (lane >= o) x += y; }
;                 if (sg < NCHUNK) cseg[sg] = run + x - v; run += __shfl(x, 63); }
;         }
.LBB0_2194:
	s_ashr_i32 s0, s67, 31
	s_lshr_b32 s0, s0, 28
	s_add_i32 s0, s67, s0
	s_and_b32 s22, s0, -16
	s_sub_i32 s22, s67, s22
	s_ashr_i32 s23, s22, 31
	s_andn2_b64 vcc, exec, s[38:39]
	s_cmp_eq_u32 s22, s98
	s_cselect_b64 vcc, exec, vcc
	s_mov_b32 s98, s22
	s_barrier
	s_cbranch_vccnz .LBB0_2200
	v_add_u32_e32 v32, s22, v252
	s_waitcnt lgkmcnt(0)
	v_ashrrev_i32_e32 v33, 31, v32
	v_lshl_add_u64 v[32:33], v[32:33], 2, s[36:37]
	global_load_dword v38, v[32:33], off
	v_add_u32_e32 v32, s22, v254
	v_mov_b32_e32 v33, v161
	v_lshl_add_u64 v[32:33], v[32:33], 2, s[36:37]
	global_load_dword v40, v[32:33], off
	v_and_b32_e32 v33, 64, v206
	v_add_u32_e32 v32, -1, v206
	v_cmp_lt_i32_e32 vcc, v32, v33
	v_add_u32_e32 v34, -2, v206
	v_add_u32_e32 v35, -4, v206
	v_cndmask_b32_e32 v32, v32, v206, vcc
	v_lshlrev_b32_e32 v32, 2, v32
	v_cmp_lt_i32_e32 vcc, v34, v33
	v_add_u32_e32 v36, -8, v206
	v_add_u32_e32 v37, -16, v206
	v_cndmask_b32_e32 v34, v34, v206, vcc
	v_cmp_lt_i32_e32 vcc, v35, v33
	v_subrev_u32_e32 v39, 32, v206
	s_waitcnt vmcnt(1)
	ds_bpermute_b32 v41, v32, v38
	v_cndmask_b32_e32 v35, v35, v206, vcc
	v_cmp_lt_i32_e32 vcc, v36, v33
	s_waitcnt vmcnt(0)
	ds_bpermute_b32 v42, v32, v40
	v_cndmask_b32_e32 v36, v36, v206, vcc
	v_cmp_lt_i32_e32 vcc, v37, v33
	s_nop 1
	v_cndmask_b32_e32 v37, v37, v206, vcc
	v_cmp_lt_i32_e32 vcc, v39, v33
	v_lshlrev_b32_e32 v33, 2, v34
	s_waitcnt lgkmcnt(1)
	v_add_f32_e32 v34, v38, v41
	v_cndmask_b32_e64 v41, v34, v38, s[10:11]
	ds_bpermute_b32 v43, v33, v41
	v_lshlrev_b32_e32 v34, 2, v35
	s_waitcnt lgkmcnt(1)
	v_add_f32_e32 v35, v40, v42
	v_cndmask_b32_e64 v42, v35, v40, s[10:11]
	ds_bpermute_b32 v44, v33, v42
	s_waitcnt lgkmcnt(1)
	v_add_f32_e32 v35, v41, v43
	v_cndmask_b32_e64 v41, v35, v41, s[12:13]
	ds_bpermute_b32 v43, v34, v41
	v_lshlrev_b32_e32 v35, 2, v36
	s_waitcnt lgkmcnt(1)
	v_add_f32_e32 v36, v42, v44
	v_cndmask_b32_e64 v42, v36, v42, s[12:13]
	ds_bpermute_b32 v44, v34, v42
	s_waitcnt lgkmcnt(1)
	v_add_f32_e32 v36, v41, v43
	v_cndmask_b32_e64 v41, v36, v41, s[14:15]
	ds_bpermute_b32 v43, v35, v41
	v_lshlrev_b32_e32 v36, 2, v37
	s_waitcnt lgkmcnt(1)
	v_add_f32_e32 v37, v42, v44
	v_cndmask_b32_e64 v37, v37, v42, s[14:15]
	ds_bpermute_b32 v42, v35, v37
	s_waitcnt lgkmcnt(1)
	v_add_f32_e32 v43, v41, v43
	v_cndmask_b32_e64 v41, v43, v41, s[16:17]
	ds_bpermute_b32 v43, v36, v41
	v_cndmask_b32_e32 v39, v39, v206, vcc
	s_waitcnt lgkmcnt(1)
	v_add_f32_e32 v42, v37, v42
	v_cndmask_b32_e64 v42, v42, v37, s[16:17]
	ds_bpermute_b32 v44, v36, v42
	s_waitcnt lgkmcnt(1)
	v_add_f32_e32 v37, v41, v43
	v_lshlrev_b32_e32 v39, 2, v39
	v_cndmask_b32_e64 v41, v37, v41, s[18:19]
	ds_bpermute_b32 v43, v39, v41
	s_waitcnt lgkmcnt(1)
	v_add_f32_e32 v44, v42, v44
	v_cndmask_b32_e64 v42, v44, v42, s[18:19]
	ds_bpermute_b32 v39, v39, v42
	v_mov_b32_e32 v37, 0
	s_waitcnt lgkmcnt(1)
	v_add_f32_e32 v43, v41, v43
	v_cndmask_b32_e64 v41, v43, v41, s[6:7]
	v_add_f32_e32 v43, 0, v41
	ds_bpermute_b32 v41, v209, v41
	v_sub_f32_e32 v38, v43, v38
	ds_write_b32 v253, v38
	s_waitcnt lgkmcnt(2)
	v_add_f32_e32 v38, v42, v39
	v_cndmask_b32_e64 v42, v38, v42, s[6:7]
	ds_bpermute_b32 v38, v209, v42
	s_waitcnt lgkmcnt(2)
	v_add_f32_e32 v39, 0, v41
	v_add_f32_e32 v41, v39, v42
	v_sub_f32_e32 v40, v41, v40
	ds_write_b32 v207, v40
	s_and_saveexec_b64 s[24:25], s[20:21]
	s_cbranch_execz .LBB0_2197
	v_add_u32_e32 v40, s22, v198
	v_mov_b32_e32 v41, v161
	v_lshl_add_u64 v[40:41], v[40:41], 2, s[36:37]
	global_load_dword v37, v[40:41], off

; __global__ void __launch_bounds__(NTHREADS, 2) fwd_megakernel(Args a) {
;     extern __shared__ __attribute__((aligned(16))) unsigned char ldsg[];
	.amdhsa_kernel _Z14fwd_megakernel4Args
		.amdhsa_group_segment_fixed_size 0
		.amdhsa_private_segment_fixed_size 0
		.amdhsa_kernarg_size 392
		.amdhsa_user_sgpr_count 2
		.amdhsa_user_sgpr_dispatch_ptr 0
		.amdhsa_user_sgpr_queue_ptr 0
		.amdhsa_user_sgpr_kernarg_segment_ptr 1
		.amdhsa_user_sgpr_dispatch_id 0
		.amdhsa_user_sgpr_kernarg_preload_length 0
		.amdhsa_user_sgpr_kernarg_preload_offset 0
		.amdhsa_user_sgpr_private_segment_size 0
		.amdhsa_uses_dynamic_stack 0
		.amdhsa_enable_private_segment 0
		.amdhsa_system_sgpr_workgroup_id_x 1
		.amdhsa_system_sgpr_workgroup_id_y 0
		.amdhsa_system_sgpr_workgroup_id_z 0
		.amdhsa_system_sgpr_workgroup_info 0
		.amdhsa_system_vgpr_workitem_id 2
		.amdhsa_next_free_vgpr 256
		.amdhsa_next_free_sgpr 99
		.amdhsa_accum_offset 256
		.amdhsa_reserve_vcc 1
		.amdhsa_float_round_mode_32 0
		.amdhsa_float_round_mode_16_64 0
		.amdhsa_float_denorm_mode_32 3
		.amdhsa_float_denorm_mode_16_64 3
		.amdhsa_dx10_clamp 1
		.amdhsa_ieee_mode 1
		.amdhsa_fp16_overflow 0
		.amdhsa_tg_split 0
		.amdhsa_exception_fp_ieee_invalid_op 0
		.amdhsa_exception_fp_denorm_src 0
		.amdhsa_exception_fp_ieee_div_zero 0
		.amdhsa_exception_fp_ieee_overflow 0
		.amdhsa_exception_fp_ieee_underflow 0
		.amdhsa_exception_fp_ieee_inexact 0
		.amdhsa_exception_int_div_zero 0
	.end_amdhsa_kernel

; __global__ void __launch_bounds__(NTHREADS, 2) fwd_megakernel(Args a) {
amdhsa.kernels:
  - .agpr_count:     0
    .args:
      - .offset:         0
        .size:           136
        .value_kind:     by_value
      - .offset:         136
        .size:           4
        .value_kind:     hidden_block_count_x
      - .offset:         140
        .size:           4
        .value_kind:     hidden_block_count_y
      - .offset:         144
        .size:           4
        .value_kind:     hidden_block_count_z
      - .offset:         148
        .size:           2
        .value_kind:     hidden_group_size_x
      - .offset:         150
        .size:           2
        .value_kind:     hidden_group_size_y
      - .offset:         152
        .size:           2
        .value_kind:     hidden_group_size_z
      - .offset:         154
        .size:           2
        .value_kind:     hidden_remainder_x
      - .offset:         156
        .size:           2
        .value_kind:     hidden_remainder_y
      - .offset:         158
        .size:           2
        .value_kind:     hidden_remainder_z
      - .offset:         176
        .size:           8
        .value_kind:     hidden_global_offset_x
      - .offset:         184
        .size:           8
        .value_kind:     hidden_global_offset_y
      - .offset:         192
        .size:           8
        .value_kind:     hidden_global_offset_z
      - .offset:         200
        .size:           2
        .value_kind:     hidden_grid_dims
      - .offset:         224
        .size:           8
        .value_kind:     hidden_multigrid_sync_arg
      - .offset:         256
        .size:           4
        .value_kind:     hidden_dynamic_lds_size
    .group_segment_fixed_size: 0
    .kernarg_segment_align: 8
    .kernarg_segment_size: 392
    .language:       OpenCL C
    .language_version:
      - 2
      - 0
    .max_flat_workgroup_size: 512
    .name:           _Z14fwd_megakernel4Args
    .private_segment_fixed_size: 0
    .sgpr_count:     105
    .sgpr_spill_count: 1
    .symbol:         _Z14fwd_megakernel4Args.kd
    .uniform_work_group_size: 1
    .uses_dynamic_stack: false
    .vgpr_count:     256
    .vgpr_spill_count: 0
    .wavefront_size: 64
